# guard for grid != 256 added; nt on deferred read-once loads
# speedup vs baseline: 1.0130x; 1.0022x over previous
.LBB0_5:
	s_or_b64 exec, exec, s[2:3]
	s_mov_b32 s32, 0
	s_cmp_eq_u32 s96, 0x100
	s_cbranch_scc1 .Lguard_ok
	s_movk_i32 s32, 0x100
.Lguard_ok:
	v_lshlrev_b32_e32 v2, 2, v0
	v_add_u32_e32 v2, 0x22080, v2
	v_writelane_b32 v3, s0, 0
	v_writelane_b32 v3, s1, 1
	v_writelane_b32 v3, s20, 2
	v_writelane_b32 v3, s76, 3
	v_writelane_b32 v3, s77, 4
	ds_write_b32 v2, v254 offset:2048
	ds_write_b32 v2, v3 offset:4096
	s_waitcnt lgkmcnt(0)

.LBB0_11:
	s_waitcnt vmcnt(0)
	v_readlane_b32 s8, v254, 17
	v_readlane_b32 s9, v254, 18
	s_barrier
	s_and_saveexec_b64 s[82:83], s[8:9]
	s_cbranch_execz .LBB0_63
	s_cmp_lg_u32 s32, 1
	s_cbranch_scc1 .Lg2_orig
	v_readlane_b32 s40, v254, 58
	v_readlane_b32 s41, v254, 59
	s_movk_i32 s46, 0x90
	s_cmp_eq_u32 s80, 0
	s_cselect_b32 s47, 1, 0
	s_lshl_b32 s46, s46, s47
	s_mov_b32 s47, 0
	buffer_wbl2 sc1
	s_waitcnt vmcnt(0)
	v_mov_b32_e32 v2, 0
	v_mov_b32_e32 v3, 1
	s_nop 4
	global_atomic_add v2, v3, s[40:41] offset:1536
	s_waitcnt vmcnt(0)

.LBB0_66:
	s_cmp_lg_u32 s32, 1
	s_cbranch_scc1 .Lg3_mode0
	v_readlane_b32 s76, v254, 58
	v_readlane_b32 s77, v254, 59
	v_readlane_b32 s78, v254, 61
	v_readlane_b32 s88, v255, 37
	v_readlane_b32 s96, v254, 56
	v_readlane_b32 s97, v254, 60
	s_nop 3
	s_add_u32 s10, s76, 0x600000
	s_addc_u32 s11, s77, 0
	v_or_b32_e32 v176, 8, v170
	v_or_b32_e32 v175, 16, v170
	v_or_b32_e32 v174, 24, v170
	v_add_u32_e32 v173, v30, v31
	s_branch .Lsec5_entry

.Lg4_nd:
	s_cmp_eq_u32 s32, 1
	s_cbranch_scc1 .LBB0_154

.LBB0_175:
	s_cmp_lg_u32 s32, 1
	s_cbranch_scc1 .Lp0_done_mode0
	s_waitcnt vmcnt(0) lgkmcnt(0)
	s_barrier
	s_mov_b32 s32, 0
	s_add_i32 s2, s97, 0x70
	s_lshl_b32 s2, s2, 11
	v_lshl_add_u32 v209, v0, 2, s2
	s_add_u32 s2, s76, 0x30c00000
	s_addc_u32 s3, s77, 0
	global_load_dword v210, v209, s[2:3]
	s_add_u32 s2, s2, 0x80000
	s_addc_u32 s3, s3, 0
	global_load_dword v211, v209, s[2:3]
	s_add_u32 s2, s2, 0x80000
	s_addc_u32 s3, s3, 0
	global_load_dword v0, v209, s[2:3]
	s_add_u32 s2, s2, 0x80000
	s_addc_u32 s3, s3, 0
	global_load_dword v1, v209, s[2:3]
	s_add_u32 s2, s2, 0x80000
	s_addc_u32 s3, s3, 0
	global_load_dword v5, v209, s[2:3]
	s_add_u32 s2, s2, 0x80000
	s_addc_u32 s3, s3, 0
	global_load_dword v6, v209, s[2:3]
	s_add_u32 s2, s2, 0x80000
	s_addc_u32 s3, s3, 0
	global_load_dword v8, v209, s[2:3]
	s_add_u32 s2, s2, 0x80000
	s_addc_u32 s3, s3, 0
	global_load_dword v36, v209, s[2:3]
	s_add_u32 s2, s2, 0x80000
	s_addc_u32 s3, s3, 0
	global_load_dword v37, v209, s[2:3]
	s_add_u32 s2, s2, 0x80000
	s_addc_u32 s3, s3, 0
	global_load_dword v38, v209, s[2:3]
	s_add_u32 s2, s2, 0x80000
	s_addc_u32 s3, s3, 0
	global_load_dword v39, v209, s[2:3]
	s_add_u32 s2, s2, 0x80000
	s_addc_u32 s3, s3, 0
	global_load_dword v40, v209, s[2:3]
	s_add_u32 s2, s2, 0x80000
	s_addc_u32 s3, s3, 0
	global_load_dword v41, v209, s[2:3]
	s_add_u32 s2, s2, 0x80000
	s_addc_u32 s3, s3, 0
	global_load_dword v42, v209, s[2:3]
	s_add_u32 s2, s2, 0x80000
	s_addc_u32 s3, s3, 0
	global_load_dword v43, v209, s[2:3]
	s_add_u32 s2, s2, 0x80000
	s_addc_u32 s3, s3, 0
	global_load_dword v44, v209, s[2:3]
	s_add_u32 s2, s2, 0x80000
	s_addc_u32 s3, s3, 0
	global_load_dword v45, v209, s[2:3]
	s_add_u32 s2, s2, 0x80000
	s_addc_u32 s3, s3, 0
	global_load_dword v50, v209, s[2:3]
	s_add_u32 s2, s2, 0x80000
	s_addc_u32 s3, s3, 0
	global_load_dword v51, v209, s[2:3]
	s_add_u32 s2, s2, 0x80000
	s_addc_u32 s3, s3, 0
	global_load_dword v52, v209, s[2:3]
	s_add_u32 s2, s2, 0x80000
	s_addc_u32 s3, s3, 0
	global_load_dword v53, v209, s[2:3]
	s_add_u32 s2, s2, 0x80000
	s_addc_u32 s3, s3, 0
	global_load_dword v54, v209, s[2:3]
	s_add_u32 s2, s2, 0x80000
	s_addc_u32 s3, s3, 0
	global_load_dword v55, v209, s[2:3]
	s_add_u32 s2, s2, 0x80000
	s_addc_u32 s3, s3, 0
	global_load_dword v56, v209, s[2:3]
	s_add_u32 s2, s2, 0x80000
	s_addc_u32 s3, s3, 0
	global_load_dword v57, v209, s[2:3]
	s_add_u32 s2, s2, 0x80000
	s_addc_u32 s3, s3, 0
	global_load_dword v62, v209, s[2:3]
	s_add_u32 s2, s2, 0x80000
	s_addc_u32 s3, s3, 0
	global_load_dword v63, v209, s[2:3]
	s_add_u32 s2, s2, 0x80000
	s_addc_u32 s3, s3, 0
	global_load_dword v64, v209, s[2:3]
	s_add_u32 s2, s2, 0x80000
	s_addc_u32 s3, s3, 0
	global_load_dword v65, v209, s[2:3]
	s_add_u32 s2, s2, 0x80000
	s_addc_u32 s3, s3, 0
	global_load_dword v70, v209, s[2:3]
	s_add_u32 s2, s2, 0x80000
	s_addc_u32 s3, s3, 0
	global_load_dword v71, v209, s[2:3]
	s_add_u32 s2, s2, 0x80000
	s_addc_u32 s3, s3, 0
	global_load_dword v72, v209, s[2:3]
	s_add_u32 s2, s2, 0x80000
	s_addc_u32 s3, s3, 0
	global_load_dword v73, v209, s[2:3]
	s_add_u32 s2, s2, 0x80000
	s_addc_u32 s3, s3, 0
	global_load_dword v82, v209, s[2:3]
	s_add_u32 s2, s2, 0x80000
	s_addc_u32 s3, s3, 0
	global_load_dword v83, v209, s[2:3]
	s_add_u32 s2, s2, 0x80000
	s_addc_u32 s3, s3, 0
	global_load_dword v84, v209, s[2:3]
	s_add_u32 s2, s2, 0x80000
	s_addc_u32 s3, s3, 0
	global_load_dword v85, v209, s[2:3]
	s_add_u32 s2, s2, 0x80000
	s_addc_u32 s3, s3, 0
	global_load_dword v88, v209, s[2:3]
	s_add_u32 s2, s2, 0x80000
	s_addc_u32 s3, s3, 0
	global_load_dword v89, v209, s[2:3]
	s_add_u32 s2, s2, 0x80000
	s_addc_u32 s3, s3, 0
	global_load_dword v94, v209, s[2:3]
	s_add_u32 s2, s2, 0x80000
	s_addc_u32 s3, s3, 0
	global_load_dword v95, v209, s[2:3]
	s_add_u32 s2, s2, 0x80000
	s_addc_u32 s3, s3, 0
	global_load_dword v96, v209, s[2:3]
	s_add_u32 s2, s2, 0x80000
	s_addc_u32 s3, s3, 0
	global_load_dword v97, v209, s[2:3]
	s_add_u32 s2, s2, 0x80000
	s_addc_u32 s3, s3, 0
	global_load_dword v102, v209, s[2:3]
	s_add_u32 s2, s2, 0x80000
	s_addc_u32 s3, s3, 0
	global_load_dword v103, v209, s[2:3]
	s_add_u32 s2, s2, 0x80000
	s_addc_u32 s3, s3, 0
	global_load_dword v104, v209, s[2:3]
	s_add_u32 s2, s2, 0x80000
	s_addc_u32 s3, s3, 0
	global_load_dword v105, v209, s[2:3]
	s_add_u32 s2, s2, 0x80000
	s_addc_u32 s3, s3, 0
	global_load_dword v122, v209, s[2:3]
	s_add_u32 s2, s2, 0x80000
	s_addc_u32 s3, s3, 0
	global_load_dword v123, v209, s[2:3]
	s_add_u32 s2, s2, 0x80000
	s_addc_u32 s3, s3, 0
	global_load_dword v124, v209, s[2:3]
	s_add_u32 s2, s2, 0x80000
	s_addc_u32 s3, s3, 0
	global_load_dword v125, v209, s[2:3]
	s_add_u32 s2, s2, 0x80000
	s_addc_u32 s3, s3, 0
	global_load_dword v170, v209, s[2:3]
	s_add_u32 s2, s2, 0x80000
	s_addc_u32 s3, s3, 0
	global_load_dword v171, v209, s[2:3]
	s_add_u32 s2, s2, 0x80000
	s_addc_u32 s3, s3, 0
	global_load_dword v172, v209, s[2:3]
	s_add_u32 s2, s2, 0x80000
	s_addc_u32 s3, s3, 0
	global_load_dword v173, v209, s[2:3]
	s_add_u32 s2, s2, 0x80000
	s_addc_u32 s3, s3, 0
	global_load_dword v174, v209, s[2:3]
	s_add_u32 s2, s2, 0x80000
	s_addc_u32 s3, s3, 0
	global_load_dword v175, v209, s[2:3]
	s_add_u32 s2, s2, 0x80000
	s_addc_u32 s3, s3, 0
	global_load_dword v195, v209, s[2:3]
	s_add_u32 s2, s2, 0x80000
	s_addc_u32 s3, s3, 0
	global_load_dword v197, v209, s[2:3]
	s_add_u32 s2, s2, 0x80000
	s_addc_u32 s3, s3, 0
	global_load_dword v254, v209, s[2:3]
	s_add_u32 s2, s2, 0x80000
	s_addc_u32 s3, s3, 0
	global_load_dword v255, v209, s[2:3]
	s_waitcnt vmcnt(0)
	v_readlane_b32 s64, v211, 0
	v_readlane_b32 s65, v211, 1
	v_readlane_b32 s66, v211, 2
	v_readlane_b32 s67, v211, 3
	v_readlane_b32 s68, v211, 4
	v_readlane_b32 s69, v211, 5
	v_readlane_b32 s70, v211, 6
	v_readlane_b32 s71, v211, 7
	v_readlane_b32 s72, v211, 8
	v_readlane_b32 s73, v211, 9
	v_readlane_b32 s74, v211, 10
	v_readlane_b32 s75, v211, 11
	v_readlane_b32 s76, v211, 12
	v_readlane_b32 s77, v211, 13
	v_readlane_b32 s78, v211, 14
	v_readlane_b32 s79, v211, 15
	v_readlane_b32 s80, v211, 16
	v_readlane_b32 s81, v211, 17
	v_readlane_b32 s82, v211, 18
	v_readlane_b32 s83, v211, 19
	v_readlane_b32 s84, v211, 20
	v_readlane_b32 s85, v211, 21
	v_readlane_b32 s86, v211, 22
	v_readlane_b32 s87, v211, 23
	v_readlane_b32 s88, v211, 24
	v_readlane_b32 s89, v211, 25
	v_readlane_b32 s90, v211, 26
	v_readlane_b32 s91, v211, 27
	v_readlane_b32 s92, v211, 28
	v_readlane_b32 s93, v211, 29
	v_readlane_b32 s94, v211, 30
	v_readlane_b32 s95, v211, 31
	v_readlane_b32 s96, v211, 32
	v_readlane_b32 s97, v211, 33
	v_readlane_b32 s0, v210, 0
	v_readlane_b32 s1, v210, 1
	v_readlane_b32 s2, v210, 2
	v_readlane_b32 s3, v210, 3
	v_readlane_b32 s4, v210, 4
	v_readlane_b32 s5, v210, 5
	v_readlane_b32 s6, v210, 6
	v_readlane_b32 s7, v210, 7
	v_readlane_b32 s8, v210, 8
	v_readlane_b32 s9, v210, 9
	v_readlane_b32 s10, v210, 10
	v_readlane_b32 s11, v210, 11
	v_readlane_b32 s12, v210, 12
	v_readlane_b32 s13, v210, 13
	v_readlane_b32 s14, v210, 14
	v_readlane_b32 s15, v210, 15
	v_readlane_b32 s16, v210, 16
	v_readlane_b32 s17, v210, 17
	v_readlane_b32 s18, v210, 18
	v_readlane_b32 s19, v210, 19
	v_readlane_b32 s20, v210, 20
	v_readlane_b32 s21, v210, 21
	v_readlane_b32 s22, v210, 22
	v_readlane_b32 s23, v210, 23
	v_readlane_b32 s24, v210, 24
	v_readlane_b32 s25, v210, 25
	v_readlane_b32 s26, v210, 26
	v_readlane_b32 s27, v210, 27
	v_readlane_b32 s28, v210, 28
	v_readlane_b32 s29, v210, 29
	v_readlane_b32 s30, v210, 30
	v_readlane_b32 s31, v210, 31
	v_readlane_b32 s33, v210, 33
	v_readlane_b32 s34, v210, 34
	v_readlane_b32 s35, v210, 35
	v_readlane_b32 s36, v210, 36
	v_readlane_b32 s37, v210, 37
	v_readlane_b32 s38, v210, 38
	v_readlane_b32 s39, v210, 39
	v_readlane_b32 s40, v210, 40
	v_readlane_b32 s41, v210, 41
	v_readlane_b32 s42, v210, 42
	v_readlane_b32 s43, v210, 43
	v_readlane_b32 s44, v210, 44
	v_readlane_b32 s45, v210, 45
	v_readlane_b32 s46, v210, 46
	v_readlane_b32 s47, v210, 47
	v_readlane_b32 s48, v210, 48
	v_readlane_b32 s49, v210, 49
	v_readlane_b32 s50, v210, 50
	v_readlane_b32 s51, v210, 51
	v_readlane_b32 s52, v210, 52
	v_readlane_b32 s53, v210, 53
	v_readlane_b32 s54, v210, 54
	v_readlane_b32 s55, v210, 55
	v_readlane_b32 s56, v210, 56
	v_readlane_b32 s57, v210, 57
	v_readlane_b32 s58, v210, 58
	v_readlane_b32 s59, v210, 59
	v_readlane_b32 s60, v210, 60
	v_readlane_b32 s61, v210, 61
	v_readlane_b32 s62, v210, 62
	v_readlane_b32 s63, v210, 63
	s_mov_b32 s32, 0
	s_nop 4
	s_branch .LBB0_361

.Lstream_call:
	s_cmp_eq_u32 s32, 0x100
	s_cbranch_scc1 .LBB0_361
	v_writelane_b32 v2, s0, 0
	v_writelane_b32 v2, s1, 1
	v_writelane_b32 v2, s2, 2
	v_writelane_b32 v2, s3, 3
	v_writelane_b32 v2, s4, 4
	v_writelane_b32 v2, s5, 5
	v_writelane_b32 v2, s6, 6
	v_writelane_b32 v2, s7, 7
	v_writelane_b32 v2, s8, 8
	v_writelane_b32 v2, s9, 9
	v_writelane_b32 v2, s10, 10
	v_writelane_b32 v2, s11, 11
	v_writelane_b32 v2, s12, 12
	v_writelane_b32 v2, s13, 13
	v_writelane_b32 v2, s14, 14
	v_writelane_b32 v2, s15, 15
	v_writelane_b32 v2, s16, 16
	v_writelane_b32 v2, s17, 17
	v_writelane_b32 v2, s18, 18
	v_writelane_b32 v2, s19, 19
	v_writelane_b32 v2, s20, 20
	v_writelane_b32 v2, s21, 21
	v_writelane_b32 v2, s22, 22
	v_writelane_b32 v2, s23, 23
	v_writelane_b32 v2, s24, 24
	v_writelane_b32 v2, s25, 25
	v_writelane_b32 v2, s26, 26
	v_writelane_b32 v2, s27, 27
	v_writelane_b32 v2, s28, 28
	v_writelane_b32 v2, s29, 29
	v_writelane_b32 v2, s30, 30
	v_writelane_b32 v2, s31, 31
	v_writelane_b32 v2, s32, 32
	v_writelane_b32 v2, s33, 33
	v_writelane_b32 v2, s34, 34
	v_writelane_b32 v2, s35, 35
	v_writelane_b32 v2, s36, 36
	v_writelane_b32 v2, s37, 37
	v_writelane_b32 v2, s38, 38
	v_writelane_b32 v2, s39, 39
	v_writelane_b32 v2, s40, 40
	v_writelane_b32 v2, s41, 41
	v_writelane_b32 v2, s42, 42
	v_writelane_b32 v2, s43, 43
	v_writelane_b32 v2, s44, 44
	v_writelane_b32 v2, s45, 45
	v_writelane_b32 v2, s46, 46
	v_writelane_b32 v2, s47, 47
	v_writelane_b32 v2, s48, 48
	v_writelane_b32 v2, s49, 49
	v_writelane_b32 v2, s50, 50
	v_writelane_b32 v2, s51, 51
	v_writelane_b32 v2, s52, 52
	v_writelane_b32 v2, s53, 53
	v_writelane_b32 v2, s54, 54
	v_writelane_b32 v2, s55, 55
	v_writelane_b32 v2, s56, 56
	v_writelane_b32 v2, s57, 57
	v_writelane_b32 v2, s58, 58
	v_writelane_b32 v2, s59, 59
	v_writelane_b32 v2, s60, 60
	v_writelane_b32 v2, s61, 61
	v_writelane_b32 v2, s62, 62
	v_writelane_b32 v2, s63, 63
	v_writelane_b32 v3, s64, 0
	v_writelane_b32 v3, s65, 1
	v_writelane_b32 v3, s66, 2
	v_writelane_b32 v3, s67, 3
	v_writelane_b32 v3, s68, 4
	v_writelane_b32 v3, s69, 5
	v_writelane_b32 v3, s70, 6
	v_writelane_b32 v3, s71, 7
	v_writelane_b32 v3, s72, 8
	v_writelane_b32 v3, s73, 9
	v_writelane_b32 v3, s74, 10
	v_writelane_b32 v3, s75, 11
	v_writelane_b32 v3, s76, 12
	v_writelane_b32 v3, s77, 13
	v_writelane_b32 v3, s78, 14
	v_writelane_b32 v3, s79, 15
	v_writelane_b32 v3, s80, 16
	v_writelane_b32 v3, s81, 17
	v_writelane_b32 v3, s82, 18
	v_writelane_b32 v3, s83, 19
	v_writelane_b32 v3, s84, 20
	v_writelane_b32 v3, s85, 21
	v_writelane_b32 v3, s86, 22
	v_writelane_b32 v3, s87, 23
	v_writelane_b32 v3, s88, 24
	v_writelane_b32 v3, s89, 25
	v_writelane_b32 v3, s90, 26
	v_writelane_b32 v3, s91, 27
	v_writelane_b32 v3, s92, 28
	v_writelane_b32 v3, s93, 29
	v_writelane_b32 v3, s94, 30
	v_writelane_b32 v3, s95, 31
	v_writelane_b32 v3, s96, 32
	v_writelane_b32 v3, s97, 33
	s_lshl_b32 s2, s97, 11
	v_lshl_add_u32 v4, v0, 2, s2
	s_add_u32 s2, s76, 0x30c00000
	s_addc_u32 s3, s77, 0
	global_store_dword v4, v2, s[2:3]
	s_add_u32 s2, s2, 0x80000
	s_addc_u32 s3, s3, 0
	global_store_dword v4, v3, s[2:3]
	s_add_u32 s2, s2, 0x80000
	s_addc_u32 s3, s3, 0
	global_store_dword v4, v0, s[2:3]
	s_add_u32 s2, s2, 0x80000
	s_addc_u32 s3, s3, 0
	global_store_dword v4, v1, s[2:3]
	s_add_u32 s2, s2, 0x80000
	s_addc_u32 s3, s3, 0
	global_store_dword v4, v5, s[2:3]
	s_add_u32 s2, s2, 0x80000
	s_addc_u32 s3, s3, 0
	global_store_dword v4, v6, s[2:3]
	s_add_u32 s2, s2, 0x80000
	s_addc_u32 s3, s3, 0
	global_store_dword v4, v8, s[2:3]
	s_add_u32 s2, s2, 0x80000
	s_addc_u32 s3, s3, 0
	global_store_dword v4, v36, s[2:3]
	s_add_u32 s2, s2, 0x80000
	s_addc_u32 s3, s3, 0
	global_store_dword v4, v37, s[2:3]
	s_add_u32 s2, s2, 0x80000
	s_addc_u32 s3, s3, 0
	global_store_dword v4, v38, s[2:3]
	s_add_u32 s2, s2, 0x80000
	s_addc_u32 s3, s3, 0
	global_store_dword v4, v39, s[2:3]
	s_add_u32 s2, s2, 0x80000
	s_addc_u32 s3, s3, 0
	global_store_dword v4, v40, s[2:3]
	s_add_u32 s2, s2, 0x80000
	s_addc_u32 s3, s3, 0
	global_store_dword v4, v41, s[2:3]
	s_add_u32 s2, s2, 0x80000
	s_addc_u32 s3, s3, 0
	global_store_dword v4, v42, s[2:3]
	s_add_u32 s2, s2, 0x80000
	s_addc_u32 s3, s3, 0
	global_store_dword v4, v43, s[2:3]
	s_add_u32 s2, s2, 0x80000
	s_addc_u32 s3, s3, 0
	global_store_dword v4, v44, s[2:3]
	s_add_u32 s2, s2, 0x80000
	s_addc_u32 s3, s3, 0
	global_store_dword v4, v45, s[2:3]
	s_add_u32 s2, s2, 0x80000
	s_addc_u32 s3, s3, 0
	global_store_dword v4, v50, s[2:3]
	s_add_u32 s2, s2, 0x80000
	s_addc_u32 s3, s3, 0
	global_store_dword v4, v51, s[2:3]
	s_add_u32 s2, s2, 0x80000
	s_addc_u32 s3, s3, 0
	global_store_dword v4, v52, s[2:3]
	s_add_u32 s2, s2, 0x80000
	s_addc_u32 s3, s3, 0
	global_store_dword v4, v53, s[2:3]
	s_add_u32 s2, s2, 0x80000
	s_addc_u32 s3, s3, 0
	global_store_dword v4, v54, s[2:3]
	s_add_u32 s2, s2, 0x80000
	s_addc_u32 s3, s3, 0
	global_store_dword v4, v55, s[2:3]
	s_add_u32 s2, s2, 0x80000
	s_addc_u32 s3, s3, 0
	global_store_dword v4, v56, s[2:3]
	s_add_u32 s2, s2, 0x80000
	s_addc_u32 s3, s3, 0
	global_store_dword v4, v57, s[2:3]
	s_add_u32 s2, s2, 0x80000
	s_addc_u32 s3, s3, 0
	global_store_dword v4, v62, s[2:3]
	s_add_u32 s2, s2, 0x80000
	s_addc_u32 s3, s3, 0
	global_store_dword v4, v63, s[2:3]
	s_add_u32 s2, s2, 0x80000
	s_addc_u32 s3, s3, 0
	global_store_dword v4, v64, s[2:3]
	s_add_u32 s2, s2, 0x80000
	s_addc_u32 s3, s3, 0
	global_store_dword v4, v65, s[2:3]
	s_add_u32 s2, s2, 0x80000
	s_addc_u32 s3, s3, 0
	global_store_dword v4, v70, s[2:3]
	s_add_u32 s2, s2, 0x80000
	s_addc_u32 s3, s3, 0
	global_store_dword v4, v71, s[2:3]
	s_add_u32 s2, s2, 0x80000
	s_addc_u32 s3, s3, 0
	global_store_dword v4, v72, s[2:3]
	s_add_u32 s2, s2, 0x80000
	s_addc_u32 s3, s3, 0
	global_store_dword v4, v73, s[2:3]
	s_add_u32 s2, s2, 0x80000
	s_addc_u32 s3, s3, 0
	global_store_dword v4, v82, s[2:3]
	s_add_u32 s2, s2, 0x80000
	s_addc_u32 s3, s3, 0
	global_store_dword v4, v83, s[2:3]
	s_add_u32 s2, s2, 0x80000
	s_addc_u32 s3, s3, 0
	global_store_dword v4, v84, s[2:3]
	s_add_u32 s2, s2, 0x80000
	s_addc_u32 s3, s3, 0
	global_store_dword v4, v85, s[2:3]
	s_add_u32 s2, s2, 0x80000
	s_addc_u32 s3, s3, 0
	global_store_dword v4, v88, s[2:3]
	s_add_u32 s2, s2, 0x80000
	s_addc_u32 s3, s3, 0
	global_store_dword v4, v89, s[2:3]
	s_add_u32 s2, s2, 0x80000
	s_addc_u32 s3, s3, 0
	global_store_dword v4, v94, s[2:3]
	s_add_u32 s2, s2, 0x80000
	s_addc_u32 s3, s3, 0
	global_store_dword v4, v95, s[2:3]
	s_add_u32 s2, s2, 0x80000
	s_addc_u32 s3, s3, 0
	global_store_dword v4, v96, s[2:3]
	s_add_u32 s2, s2, 0x80000
	s_addc_u32 s3, s3, 0
	global_store_dword v4, v97, s[2:3]
	s_add_u32 s2, s2, 0x80000
	s_addc_u32 s3, s3, 0
	global_store_dword v4, v102, s[2:3]
	s_add_u32 s2, s2, 0x80000
	s_addc_u32 s3, s3, 0
	global_store_dword v4, v103, s[2:3]
	s_add_u32 s2, s2, 0x80000
	s_addc_u32 s3, s3, 0
	global_store_dword v4, v104, s[2:3]
	s_add_u32 s2, s2, 0x80000
	s_addc_u32 s3, s3, 0
	global_store_dword v4, v105, s[2:3]
	s_add_u32 s2, s2, 0x80000
	s_addc_u32 s3, s3, 0
	global_store_dword v4, v122, s[2:3]
	s_add_u32 s2, s2, 0x80000
	s_addc_u32 s3, s3, 0
	global_store_dword v4, v123, s[2:3]
	s_add_u32 s2, s2, 0x80000
	s_addc_u32 s3, s3, 0
	global_store_dword v4, v124, s[2:3]
	s_add_u32 s2, s2, 0x80000
	s_addc_u32 s3, s3, 0
	global_store_dword v4, v125, s[2:3]
	s_add_u32 s2, s2, 0x80000
	s_addc_u32 s3, s3, 0
	global_store_dword v4, v170, s[2:3]
	s_add_u32 s2, s2, 0x80000
	s_addc_u32 s3, s3, 0
	global_store_dword v4, v171, s[2:3]
	s_add_u32 s2, s2, 0x80000
	s_addc_u32 s3, s3, 0
	global_store_dword v4, v172, s[2:3]
	s_add_u32 s2, s2, 0x80000
	s_addc_u32 s3, s3, 0
	global_store_dword v4, v173, s[2:3]
	s_add_u32 s2, s2, 0x80000
	s_addc_u32 s3, s3, 0
	global_store_dword v4, v174, s[2:3]
	s_add_u32 s2, s2, 0x80000
	s_addc_u32 s3, s3, 0
	global_store_dword v4, v175, s[2:3]
	s_add_u32 s2, s2, 0x80000
	s_addc_u32 s3, s3, 0
	global_store_dword v4, v195, s[2:3]
	s_add_u32 s2, s2, 0x80000
	s_addc_u32 s3, s3, 0
	global_store_dword v4, v197, s[2:3]
	s_add_u32 s2, s2, 0x80000
	s_addc_u32 s3, s3, 0
	global_store_dword v4, v254, s[2:3]
	s_add_u32 s2, s2, 0x80000
	s_addc_u32 s3, s3, 0
	global_store_dword v4, v255, s[2:3]
	s_waitcnt vmcnt(0)
	v_lshlrev_b32_e32 v4, 2, v0
	v_add_u32_e32 v4, 0x22080, v4
	ds_read_b32 v7, v4 offset:4096
	ds_read_b32 v254, v4 offset:2048
	s_waitcnt lgkmcnt(0)
	s_sub_i32 s2, s97, 0x70
	v_readlane_b32 s0, v7, 0
	v_readlane_b32 s1, v7, 1
	v_readlane_b32 s20, v7, 2
	v_readlane_b32 s76, v7, 3
	v_readlane_b32 s77, v7, 4
	s_movk_i32 s96, 0x90
	s_mov_b32 s97, s2
	s_mov_b32 s32, 1
	s_nop 4
	s_branch .Lmode_reentry

.LBB0_649:
	s_or_b64 exec, exec, s[0:1]
	v_readlane_b32 s0, v254, 10
	v_readlane_b32 s2, v254, 12
	s_cmp_eq_u32 s32, 0x100
	s_cbranch_scc1 .Lp5_orig
	s_cmpk_lt_i32 s97, 0x70
	s_cbranch_scc1 .Lp5_skip
.Lp5_orig:
	s_bitcmp0_b32 s2, 0

.LBB0_738:
	s_mov_b32 s3, s97
	s_cmp_eq_u32 s32, 0x100
	s_cbranch_scc1 .Li8_s1
	s_cmpk_lt_i32 s97, 0x70
	s_cselect_b32 s3, 0, 0x2a0
	s_add_i32 s3, s3, s97
.Li8_s1:
	s_cmpk_lt_i32 s3, 0x3e0
	s_cselect_b64 s[0:1], -1, 0
	s_cmpk_gt_i32 s3, 0x3df
	v_readfirstlane_b32 s6, v0
	s_cbranch_scc1 .LBB0_743
	s_and_b32 s2, s3, 7
	s_mul_i32 s5, s2, 0x7c
	s_lshr_b32 s2, s3, 3
	s_add_i32 s5, s5, s2
	s_cmpk_gt_i32 s5, 0x37f
	s_cbranch_scc0 .LBB0_741
	s_add_i32 s2, s5, 0xfffffc80
	s_lshr_b32 s3, s2, 4
	s_and_b32 s4, s5, 15
	s_cmp_lt_u32 s2, 32
	s_cselect_b32 s2, 14, 28
	s_add_i32 s14, s2, s3
	s_add_i32 s2, s4, 24
	s_cmp_lt_u32 s4, 8
	s_cselect_b32 s4, s4, s2
	s_cbranch_execz .LBB0_742
	s_branch .LBB0_743

.LBB0_749:
	s_add_i32 s53, s53, 1
	v_readlane_b32 s16, v254, 56
	v_readlane_b32 s6, v254, 60
	s_nop 0
	s_cmp_eq_u32 s32, 0x100
	s_cbranch_scc0 .Li8_en
	s_mul_i32 s5, s53, s16
	s_add_i32 s5, s5, s6
	s_branch .Li8_join
.Li8_en:
	s_cmpk_lt_i32 s6, 0x70
	s_cbranch_scc0 .Li8_clsB
	s_mul_i32 s5, s53, 0x70
	s_add_i32 s5, s5, s6
	s_cmpk_lt_i32 s53, 7
	s_cselect_b32 s5, s5, 0x3e0
	s_branch .Li8_join
